# v54 + mLSTM seq loop: rename temp v83->v200 (was WAW with prefetch load dest v[80:83]) and drop the resulting s_waitcnt vmcnt(0) that exposed the prefetch latency at P2 start
# speedup vs baseline: 1.0045x; 1.0045x over previous
; #define LAS __attribute__((address_space(3)))
; __device__ __forceinline__ bf16_t f2bf(float f) { return (bf16_t)(pk2(f, 0.f) & 0xffffu); }
; __device__ __forceinline__ float fast_rcp(float x) { return __builtin_amdgcn_rcpf(x); }
; #define MFMA32(a, b, c) __builtin_amdgcn_mfma_f32_32x32x16_bf16((a), (b), (c), 0, 0, 0)
; __device__ __forceinline__ void mlstm_unit(const Params& p, int l, int b, int h, LAS unsigned char* lds) {
;     ...
;         {
;             const int tblk = w4 & 1, vblk = w4 >> 1;
;             f32x16 a1, a2;
; #pragma unroll
;             for (int i = 0; i < 16; ++i) { a1[i] = 0.f; a2[i] = 0.f; }
; #pragma unroll
;             for (int c = 0; c < 4; ++c) { const bf16x8 bv = lds_rd16(L + ML_VT + (32 * vblk + r32) * 144 + hi * 16 + c * 32), as = lds_rd16(L + ML_SW + (32 * tblk + r32) * 144 + hi * 16 + c * 32);
;                 const bf16x8 aq = lds_rd16(L + ML_QS + (32 * tblk + r32) * 144 + hi * 16 + c * 32), bc2 = lds_rd16(CTc + (32 * vblk + r32) * 144 + hi * 16 + c * 32);
;                 a1 = MFMA32(as, bv, a1); a2 = MFMA32(aq, bc2, a2); }
;             const int tau0 = cidx * 64; const size_t rowc = tau0 < CTX ? (size_t)(ctxrow0 + tau0) : (size_t)(latrow0 + tau0 - CTX);
;             bf16_t* hp = HX + rowc * 256 + h * 64 + 32 * vblk + r32;
; #pragma unroll
;             for (int ig = 0; ig < 4; ++ig) { const int t0 = 32 * tblk + 8 * ig + 4 * hi;
;                 const f32x4 d0 = *(const LAS f32x4*)(L + ML_TAB + T_DP0 + t0 * 4), d1 = *(const LAS f32x4*)(L + ML_TAB + T_DP1 + t0 * 4), di = *(const LAS f32x4*)(L + ML_TAB + T_DI + t0 * 4),
;                             w4v = *(const LAS f32x4*)(L + ML_TAB + T_WP + t0 * 4), em = *(const LAS f32x4*)(L + ML_TAB + T_EMT + t0 * 4);
; #pragma unroll
;                 for (int e = 0; e < 4; ++e) { const float den = d0[e] + d1[e] + w4v[e] * di[e]; const float dn = fmaxf(fabsf(den), em[e]);
;                     const float hv = (a1[4 * ig + e] + w4v[e] * a2[4 * ig + e]) * fast_rcp(dn); hp[(size_t)(t0 + e) * 256] = f2bf(hv); } }
.LBB0_456:
	s_and_b64 s[76:77], s[76:77], exec
	s_waitcnt lgkmcnt(0)
	s_barrier
	s_cselect_b32 s78, s88, 0xd800
	ds_read_b128 v[16:19], v135 offset:36864
	ds_read_b128 v[20:23], v116 offset:27648
	ds_read_b128 v[106:109], v116 offset:27680
	v_add_f32_e32 v136, v32, v33
	v_add_u32_e32 v85, s78, v116
	ds_read_b128 v[32:35], v135
	ds_read_b128 v[138:141], v135 offset:32
	ds_read_b128 v[36:39], v85
	ds_read_b128 v[142:145], v85 offset:32
	ds_read_b128 v[146:149], v135 offset:36896
	s_waitcnt lgkmcnt(6)
	v_mfma_f32_32x32x16_bf16 v[16:31], v[16:19], v[20:23], 0
	ds_read_b128 v[162:165], v116 offset:27712
	ds_read_b128 v[166:169], v135 offset:36928
	ds_read_b128 v[170:173], v135 offset:64
	ds_read_b128 v[174:177], v85 offset:64
	ds_read_b128 v[178:181], v116 offset:27744
	ds_read_b128 v[182:185], v135 offset:36960
	ds_read_b128 v[186:189], v135 offset:96
	ds_read_b128 v[190:193], v85 offset:96
	s_cmp_gt_u32 s90, 3
	s_cselect_b32 s64, 0x47, 3
	s_add_i32 s64, s64, s47
	s_addk_i32 s64, 0xffba
	s_and_b64 s[76:77], s[4:5], exec
	s_cselect_b32 s64, s90, s64
	s_lshl_b32 s76, s64, 6
	s_waitcnt lgkmcnt(10)
	v_mfma_f32_32x32x16_bf16 v[32:47], v[32:35], v[36:39], 0
	s_add_i32 s78, s76, s66
	s_ashr_i32 s77, s78, 31
	s_add_i32 s76, s76, s84
	s_cmp_lt_i32 s64, 4
	s_cselect_b32 s77, s77, 0
	s_cselect_b32 s76, s78, s76
	s_lshl_b64 s[76:77], s[76:77], 9
	s_waitcnt lgkmcnt(8)
	v_mfma_f32_32x32x16_bf16 v[16:31], v[146:149], v[106:109], v[16:31]
	s_movk_i32 s64, 0x1000
	s_xor_b32 s44, s44, 1
	s_add_i32 s47, s47, -1
	s_cmp_eq_u32 s47, 2
	s_mov_b32 s90, s92
	v_mfma_f32_32x32x16_bf16 v[32:47], v[138:141], v[142:145], v[32:47]
	s_waitcnt lgkmcnt(6)
	v_mfma_f32_32x32x16_bf16 v[16:31], v[166:169], v[162:165], v[16:31]
	s_waitcnt lgkmcnt(4)
	v_mfma_f32_32x32x16_bf16 v[32:47], v[170:173], v[174:177], v[32:47]
	v_add_u32_e32 v85, s46, v122
	s_waitcnt lgkmcnt(2)
	v_mfma_f32_32x32x16_bf16 v[16:31], v[182:185], v[178:181], v[16:31]
	ds_read_b128 v[138:141], v85
	v_add_u32_e32 v85, s2, v122
	v_add_u32_e32 v108, s33, v122
	v_lshl_add_u64 v[106:107], v[98:99], 0, s[76:77]
	s_waitcnt lgkmcnt(1)
	v_mfma_f32_32x32x16_bf16 v[32:47], v[186:189], v[190:193], v[32:47]
	ds_read_b128 v[142:145], v85
	v_add_u32_e32 v85, s67, v122
	ds_read_b128 v[146:149], v85
	ds_read_b128 v[84:87], v84 offset:65024
	ds_read_b128 v[150:153], v108
	s_waitcnt lgkmcnt(3)
	v_add_f32_e32 v108, v138, v142
	s_waitcnt lgkmcnt(1)
	v_fmac_f32_e32 v108, v146, v84
	s_waitcnt lgkmcnt(0)
	v_max_f32_e32 v109, v150, v150
	v_max_f32_e64 v108, |v108|, v109
	v_fma_f32 v16, v32, v84, v16
	v_rcp_f32_e32 v32, v108
	v_lshl_add_u64 v[108:109], v[106:107], 0, v[160:161]
	v_fma_f32 v17, v33, v85, v17
	v_add_u32_e32 v84, s67, v123
	v_mul_f32_e32 v16, v16, v32
	v_cvt_pk_bf16_f32 v16, v16, s0
	global_store_short v[108:109], v16, off
	v_add_f32_e32 v16, v139, v143
	v_fmac_f32_e32 v16, v147, v85
	v_max_f32_e32 v32, v151, v151
	v_max_f32_e64 v16, |v16|, v32
	v_rcp_f32_e32 v16, v16
	v_add_u32_e32 v32, s2, v123
	v_mul_f32_e32 v16, v17, v16
	v_cvt_pk_bf16_f32 v16, v16, s0
	global_store_short v[108:109], v16, off offset:512
	v_add_f32_e32 v16, v140, v144
	v_fmac_f32_e32 v16, v148, v86
	v_max_f32_e32 v17, v152, v152
	v_max_f32_e64 v16, |v16|, v17
	v_rcp_f32_e32 v16, v16
	v_fma_f32 v17, v34, v86, v18
	v_mul_f32_e32 v16, v17, v16
	v_cvt_pk_bf16_f32 v16, v16, s0
	global_store_short v[108:109], v16, off offset:1024
	v_add_f32_e32 v16, v141, v145
	v_fmac_f32_e32 v16, v149, v87
	v_max_f32_e32 v17, v153, v153
	v_max_f32_e64 v16, |v16|, v17
	v_rcp_f32_e32 v16, v16
	v_fma_f32 v17, v35, v87, v19
	ds_read_b128 v[32:35], v32
	v_mul_f32_e32 v16, v17, v16
	v_cvt_pk_bf16_f32 v16, v16, s0
	global_store_short v[108:109], v16, off offset:1536
	v_add_u32_e32 v16, s46, v123
	ds_read_b128 v[16:19], v16
	ds_read_b128 v[84:87], v84
	ds_read_b128 v[138:141], v103 offset:65024
	v_add_u32_e32 v103, s33, v123
	ds_read_b128 v[142:145], v103
	v_mov_b32_e32 v103, v161
	s_waitcnt lgkmcnt(3)
	v_add_f32_e32 v16, v16, v32
	s_waitcnt lgkmcnt(1)
	v_fmac_f32_e32 v16, v84, v138
	v_fma_f32 v20, v36, v138, v20
	s_waitcnt lgkmcnt(0)
; #define LAS __attribute__((address_space(3)))
; __device__ __forceinline__ bf16_t f2bf(float f) { return (bf16_t)(pk2(f, 0.f) & 0xffffu); }
; __device__ __forceinline__ float fast_rcp(float x) { return __builtin_amdgcn_rcpf(x); }
; __device__ __forceinline__ void mlstm_unit(const Params& p, int l, int b, int h, LAS unsigned char* lds) {
;     ...
;             const int tau0 = cidx * 64; const size_t rowc = tau0 < CTX ? (size_t)(ctxrow0 + tau0) : (size_t)(latrow0 + tau0 - CTX);
;             bf16_t* hp = HX + rowc * 256 + h * 64 + 32 * vblk + r32;
; #pragma unroll
;             for (int ig = 0; ig < 4; ++ig) { const int t0 = 32 * tblk + 8 * ig + 4 * hi;
;                 const f32x4 d0 = *(const LAS f32x4*)(L + ML_TAB + T_DP0 + t0 * 4), d1 = *(const LAS f32x4*)(L + ML_TAB + T_DP1 + t0 * 4), di = *(const LAS f32x4*)(L + ML_TAB + T_DI + t0 * 4),
;                             w4v = *(const LAS f32x4*)(L + ML_TAB + T_WP + t0 * 4), em = *(const LAS f32x4*)(L + ML_TAB + T_EMT + t0 * 4);
; #pragma unroll
;                 for (int e = 0; e < 4; ++e) { const float den = d0[e] + d1[e] + w4v[e] * di[e]; const float dn = fmaxf(fabsf(den), em[e]);
;                     const float hv = (a1[4 * ig + e] + w4v[e] * a2[4 * ig + e]) * fast_rcp(dn); hp[(size_t)(t0 + e) * 256] = f2bf(hv); } }
;         }
	v_max_f32_e32 v32, v142, v142
	v_max_f32_e64 v16, |v16|, v32
	v_rcp_f32_e32 v16, v16
	v_lshl_add_u64 v[146:147], v[106:107], 0, v[102:103]
	v_add_f32_e32 v18, v18, v34
	v_fmac_f32_e32 v18, v86, v140
	v_mul_f32_e32 v16, v20, v16
	v_cvt_pk_bf16_f32 v16, v16, s0
	global_store_short v[146:147], v16, off
	v_add_f32_e32 v16, v17, v33
	v_fmac_f32_e32 v16, v85, v139
	v_max_f32_e32 v17, v143, v143
	v_max_f32_e64 v16, |v16|, v17
	v_rcp_f32_e32 v16, v16
	v_fma_f32 v17, v37, v139, v21
	v_add_u32_e32 v32, s67, v124
	v_add_u32_e32 v84, s33, v124
	v_mul_f32_e32 v16, v17, v16
	v_cvt_pk_bf16_f32 v20, v16, s0
	v_add_co_u32_e32 v16, vcc, s64, v108
	s_movk_i32 s64, 0x2000
	s_nop 0
	v_addc_co_u32_e32 v17, vcc, 0, v109, vcc
	global_store_short v[16:17], v20, off offset:512
	v_max_f32_e32 v20, v144, v144
	v_max_f32_e64 v18, |v18|, v20
	v_rcp_f32_e32 v18, v18
	v_fma_f32 v20, v38, v140, v22
	v_mul_f32_e32 v18, v20, v18
	v_cvt_pk_bf16_f32 v18, v18, s0
	global_store_short v[16:17], v18, off offset:1024
	v_add_f32_e32 v18, v19, v35
	v_fmac_f32_e32 v18, v87, v141
	v_max_f32_e32 v19, v145, v145
	v_max_f32_e64 v18, |v18|, v19
	v_rcp_f32_e32 v18, v18
	v_fma_f32 v19, v39, v141, v23
	v_add_u32_e32 v20, s2, v124
	ds_read_b128 v[20:23], v20
	v_mul_f32_e32 v18, v19, v18
	v_cvt_pk_bf16_f32 v18, v18, s0
	global_store_short v[16:17], v18, off offset:1536
	v_add_u32_e32 v16, s46, v124
	ds_read_b128 v[16:19], v16
	ds_read_b128 v[32:35], v32
	ds_read_b128 v[36:39], v105 offset:65024
	ds_read_b128 v[84:87], v84
	v_mov_b32_e32 v105, v161
	v_lshl_add_u64 v[138:139], v[106:107], 0, v[104:105]
	s_waitcnt lgkmcnt(3)
	v_add_f32_e32 v16, v16, v20
	s_waitcnt lgkmcnt(1)
	v_fmac_f32_e32 v16, v32, v36
	s_waitcnt lgkmcnt(0)
	v_max_f32_e32 v20, v84, v84
	v_max_f32_e64 v16, |v16|, v20
	v_rcp_f32_e32 v16, v16
	v_fma_f32 v20, v40, v36, v24
	v_add_f32_e32 v18, v18, v22
	v_fmac_f32_e32 v18, v34, v38
	v_mul_f32_e32 v16, v20, v16
	v_cvt_pk_bf16_f32 v16, v16, s0
	global_store_short v[138:139], v16, off
	v_add_f32_e32 v16, v17, v21
	v_fmac_f32_e32 v16, v33, v37
	v_max_f32_e32 v17, v85, v85
	v_max_f32_e64 v16, |v16|, v17
	v_rcp_f32_e32 v16, v16
	v_fma_f32 v17, v41, v37, v25
	v_add_u32_e32 v24, s67, v125
	v_add_u32_e32 v36, s33, v125
	v_mul_f32_e32 v16, v17, v16
	v_cvt_pk_bf16_f32 v20, v16, s0
	v_add_co_u32_e32 v16, vcc, s64, v108
	v_lshl_add_u64 v[40:41], v[100:101], 1, v[106:107]
	s_nop 0
	v_addc_co_u32_e32 v17, vcc, 0, v109, vcc
	global_store_short v[16:17], v20, off offset:512
	v_max_f32_e32 v20, v86, v86
	v_max_f32_e64 v18, |v18|, v20
	v_rcp_f32_e32 v18, v18
	v_fma_f32 v20, v42, v38, v26
	s_movk_i32 s64, 0x3000
	v_mul_f32_e32 v18, v20, v18
	v_cvt_pk_bf16_f32 v18, v18, s0
	global_store_short v[16:17], v18, off offset:1024
	v_add_f32_e32 v18, v19, v23
	v_fmac_f32_e32 v18, v35, v39
	v_max_f32_e32 v19, v87, v87
	v_max_f32_e64 v18, |v18|, v19
	v_rcp_f32_e32 v18, v18
	v_fma_f32 v19, v43, v39, v27
	v_add_u32_e32 v20, s2, v125
	ds_read_b128 v[20:23], v20
	v_mul_f32_e32 v18, v19, v18
	v_cvt_pk_bf16_f32 v18, v18, s0
	global_store_short v[16:17], v18, off offset:1536
	v_add_u32_e32 v16, s46, v125
	ds_read_b128 v[16:19], v16
	ds_read_b128 v[24:27], v24
	ds_read_b128 v[32:35], v200 offset:65024
	ds_read_b128 v[36:39], v36
	s_waitcnt lgkmcnt(3)
	v_add_f32_e32 v16, v16, v20
	s_waitcnt lgkmcnt(1)
	v_fmac_f32_e32 v16, v24, v32
	s_waitcnt lgkmcnt(0)
	v_max_f32_e32 v20, v36, v36
	v_max_f32_e64 v16, |v16|, v20
	v_rcp_f32_e32 v16, v16
	v_fma_f32 v20, v44, v32, v28
	v_add_f32_e32 v18, v18, v22
	v_fmac_f32_e32 v18, v26, v34
	v_mul_f32_e32 v16, v20, v16
	v_cvt_pk_bf16_f32 v16, v16, s0
	global_store_short v[40:41], v16, off
	v_add_f32_e32 v16, v17, v21
	v_fmac_f32_e32 v16, v25, v33
	v_max_f32_e32 v17, v37, v37
	v_max_f32_e64 v16, |v16|, v17
	v_rcp_f32_e32 v16, v16
	v_fma_f32 v17, v45, v33, v29
	v_fmac_f32_e32 v31, v47, v35
	v_mul_f32_e32 v16, v17, v16
	v_cvt_pk_bf16_f32 v20, v16, s0
	v_add_co_u32_e32 v16, vcc, s64, v108
	s_nop 1
	v_addc_co_u32_e32 v17, vcc, 0, v109, vcc
	global_store_short v[16:17], v20, off offset:512
	v_max_f32_e32 v20, v38, v38
	v_max_f32_e64 v18, |v18|, v20
	v_rcp_f32_e32 v18, v18
	v_fma_f32 v20, v46, v34, v30
	v_mul_f32_e32 v18, v20, v18
	v_cvt_pk_bf16_f32 v18, v18, s0
	global_store_short v[16:17], v18, off offset:1024
	v_add_f32_e32 v18, v19, v23
	v_fmac_f32_e32 v18, v27, v35
	v_max_f32_e32 v19, v39, v39
	v_max_f32_e64 v18, |v18|, v19
	v_rcp_f32_e32 v18, v18
	s_nop 0
	v_mul_f32_e32 v18, v31, v18
	v_cvt_pk_bf16_f32 v18, v18, s0
	global_store_short v[16:17], v18, off offset:1536
	s_waitcnt lgkmcnt(0)
	s_barrier
	s_cbranch_scc1 .LBB0_472

; #define LAS __attribute__((address_space(3)))
; __device__ __forceinline__ unsigned pk2(float lo, float hi) { f32x2_t v = {lo, hi}; bf16x2_t b = __builtin_convertvector(v, bf16x2_t); return __builtin_bit_cast(unsigned, b); }
; __device__ __forceinline__ float fast_exp(float x) { return __builtin_amdgcn_exp2f(x * 1.4426950408889634f); }
; #define MFMA32(a, b, c) __builtin_amdgcn_mfma_f32_32x32x16_bf16((a), (b), (c), 0, 0, 0)
; __device__ __forceinline__ void mlstm_unit(const Params& p, int l, int b, int h, LAS unsigned char* lds) {
;     ...
;         {
;             const int sblk = w4 & 1, tblk = w4 >> 1;
;             f32x16 st;
; #pragma unroll
;             for (int i = 0; i < 16; ++i) st[i] = 0.f;
; #pragma unroll
;             for (int c = 0; c < 4; ++c) { const bf16x8 af = lds_rd16(L + ML_KS + (32 * sblk + r32) * 144 + hi * 16 + c * 32), bfr = lds_rd16(L + ML_QS + (32 * tblk + r32) * 144 + hi * 16 + c * 32); st = MFMA32(af, bfr, st); }
;             const int t = 32 * tblk + r32; const float At = tb[T_BIGA / 4 + t];
;             float dsum = 0.f;
; #pragma unroll
;             for (int ig = 0; ig < 4; ++ig) { const int s0 = 32 * sblk + 8 * ig + 4 * hi; const f32x4 a4 = *(const LAS f32x4*)(L + ML_TAB + T_A + s0 * 4);
;                 float w[4];
; #pragma unroll
;                 for (int e = 0; e < 4; ++e) { const int s = s0 + e; const bool valid = g ? (s >= t) : (s <= t); const float ex = fast_exp(fminf(a4[e] - At, 0.f)); w[e] = valid ? st[4 * ig + e] * ex : 0.f; dsum += w[e]; }
;                 u32x2 pw; pw.x = pk2(w[0], w[1]); pw.y = pk2(w[2], w[3]); *(LAS u32x2*)(L + ML_SW + t * 144 + s0 * 2) = pw; }
;             dsum += __shfl_xor(dsum, 32);
;             if (hi == 0) *(LAS float*)(L + ML_TAB + (sblk ? T_DP1 : T_DP0) + t * 4) = dsum;
;         }
.LBB0_464:
	s_waitcnt lgkmcnt(0)
	s_barrier
	ds_read_b128 v[16:19], v135 offset:9216
	ds_read_b128 v[34:37], v135 offset:9248
	ds_read_b128 v[20:23], v116
	ds_read_b128 v[38:41], v116 offset:32
	ds_read_b128 v[162:165], v135 offset:9280
	ds_read_b128 v[166:169], v116 offset:64
	ds_read_b128 v[170:173], v135 offset:9312
	ds_read_b128 v[174:177], v116 offset:96
	v_add_u32_e32 v84, s85, v122
	v_add_u32_e32 v103, s85, v123
	v_add_u32_e32 v105, s85, v124
	s_waitcnt lgkmcnt(5)
	v_mfma_f32_32x32x16_bf16 v[16:31], v[16:19], v[20:23], 0
	v_add_u32_e32 v200, s85, v125
	ds_read_b32 v178, v127 offset:64768
	ds_read_b128 v[180:183], v84 offset:64512
	ds_read_b128 v[184:187], v103 offset:64512
	ds_read_b128 v[188:191], v105 offset:64512
	ds_read_b128 v[196:199], v200 offset:64512
	s_waitcnt lgkmcnt(9)
	v_mfma_f32_32x32x16_bf16 v[16:31], v[34:37], v[38:41], v[16:31]
	s_waitcnt lgkmcnt(7)
	v_mfma_f32_32x32x16_bf16 v[16:31], v[162:165], v[166:169], v[16:31]
	s_waitcnt lgkmcnt(5)
	v_mfma_f32_32x32x16_bf16 v[16:31], v[170:173], v[174:177], v[16:31]
	s_waitcnt lgkmcnt(0)
	v_sub_f32_e32 v35, v180, v178
	v_sub_f32_e32 v36, v181, v178
	v_min_f32_e32 v36, 0, v36
	v_mul_f32_e32 v36, 0x3fb8aa3b, v36
	v_exp_f32_e32 v36, v36
	v_min_f32_e32 v35, 0, v35
	v_mul_f32_e32 v35, 0x3fb8aa3b, v35
	v_exp_f32_e32 v35, v35
	s_nop 0
	v_mul_f32_e32 v17, v17, v36
	v_sub_f32_e32 v36, v182, v178
	v_min_f32_e32 v36, 0, v36
	v_mul_f32_e32 v36, 0x3fb8aa3b, v36
	v_exp_f32_e32 v36, v36
	v_mul_f32_e32 v16, v16, v35
	v_cndmask_b32_e64 v16, 0, v16, s[8:9]
	v_add_f32_e32 v35, 0, v16
	v_mul_f32_e32 v18, v18, v36
	v_sub_f32_e32 v36, v183, v178
	v_min_f32_e32 v36, 0, v36
	v_mul_f32_e32 v36, 0x3fb8aa3b, v36
	v_exp_f32_e32 v36, v36
	v_cndmask_b32_e64 v17, 0, v17, s[10:11]
	v_cndmask_b32_e64 v18, 0, v18, s[12:13]
	v_add_f32_e32 v35, v17, v35
	v_mul_f32_e32 v19, v19, v36
	v_cndmask_b32_e64 v19, 0, v19, s[14:15]
	v_cvt_pk_bf16_f32 v16, v16, v17
	v_cvt_pk_bf16_f32 v17, v18, v19
	v_add_f32_e32 v35, v18, v35
	ds_write_b64 v128, v[16:17] offset:36864
	v_add_f32_e32 v35, v19, v35
	v_sub_f32_e32 v16, v184, v178
	v_min_f32_e32 v16, 0, v16
	v_sub_f32_e32 v17, v185, v178
	v_sub_f32_e32 v18, v186, v178
	v_sub_f32_e32 v19, v187, v178
	v_mul_f32_e32 v16, 0x3fb8aa3b, v16
	v_min_f32_e32 v17, 0, v17
	v_min_f32_e32 v18, 0, v18
	v_min_f32_e32 v19, 0, v19
	v_exp_f32_e32 v16, v16
	v_mul_f32_e32 v17, 0x3fb8aa3b, v17
	v_mul_f32_e32 v18, 0x3fb8aa3b, v18
	v_mul_f32_e32 v19, 0x3fb8aa3b, v19
	v_exp_f32_e32 v17, v17
	v_exp_f32_e32 v18, v18
	v_exp_f32_e32 v19, v19
	v_mul_f32_e32 v16, v20, v16
	v_cndmask_b32_e64 v16, 0, v16, s[16:17]
	v_mul_f32_e32 v17, v21, v17
	v_mul_f32_e32 v18, v22, v18
	v_mul_f32_e32 v19, v23, v19
	v_add_f32_e32 v20, v16, v35
	v_cndmask_b32_e64 v17, 0, v17, s[18:19]
	v_cndmask_b32_e64 v18, 0, v18, s[20:21]
	v_cndmask_b32_e64 v19, 0, v19, s[22:23]
	v_add_f32_e32 v20, v17, v20
	v_cvt_pk_bf16_f32 v16, v16, v17
	v_cvt_pk_bf16_f32 v17, v18, v19
	v_add_f32_e32 v20, v18, v20
	ds_write_b64 v129, v[16:17] offset:36864
	v_add_f32_e32 v20, v19, v20
	v_sub_f32_e32 v16, v188, v178
	v_min_f32_e32 v16, 0, v16
	v_sub_f32_e32 v17, v189, v178
	v_sub_f32_e32 v18, v190, v178
	v_sub_f32_e32 v19, v191, v178
	v_mul_f32_e32 v16, 0x3fb8aa3b, v16
	v_min_f32_e32 v17, 0, v17
	v_min_f32_e32 v18, 0, v18
	v_min_f32_e32 v19, 0, v19
	v_exp_f32_e32 v16, v16
	v_mul_f32_e32 v17, 0x3fb8aa3b, v17
	v_mul_f32_e32 v18, 0x3fb8aa3b, v18
	v_mul_f32_e32 v19, 0x3fb8aa3b, v19
	v_exp_f32_e32 v17, v17
	v_exp_f32_e32 v18, v18
	v_exp_f32_e32 v19, v19
	v_mul_f32_e32 v16, v24, v16
	v_cndmask_b32_e64 v16, 0, v16, s[24:25]
	v_mul_f32_e32 v17, v25, v17
	v_mul_f32_e32 v18, v26, v18
	v_mul_f32_e32 v19, v27, v19
	v_add_f32_e32 v20, v16, v20
	v_cndmask_b32_e64 v17, 0, v17, s[26:27]
	v_cndmask_b32_e64 v18, 0, v18, s[28:29]
	v_cndmask_b32_e64 v19, 0, v19, s[30:31]
	v_add_f32_e32 v20, v17, v20
	v_cvt_pk_bf16_f32 v16, v16, v17
	v_cvt_pk_bf16_f32 v17, v18, v19
	v_add_f32_e32 v20, v18, v20
	ds_write_b64 v131, v[16:17] offset:36864
	v_add_f32_e32 v20, v19, v20
	v_sub_f32_e32 v16, v196, v178
	v_min_f32_e32 v16, 0, v16
	v_sub_f32_e32 v18, v198, v178
	v_mul_f32_e32 v16, 0x3fb8aa3b, v16
	v_min_f32_e32 v18, 0, v18
	v_exp_f32_e32 v16, v16
	v_mul_f32_e32 v18, 0x3fb8aa3b, v18
	v_exp_f32_e32 v18, v18
	v_sub_f32_e32 v17, v197, v178
	v_mul_f32_e32 v16, v28, v16
	v_cndmask_b32_e64 v21, 0, v16, s[34:35]
	v_min_f32_e32 v17, 0, v17
	v_mul_f32_e32 v18, v30, v18
	v_add_f32_e32 v16, v21, v20
	v_mul_f32_e32 v17, 0x3fb8aa3b, v17
	v_cndmask_b32_e64 v20, 0, v18, s[38:39]
	v_sub_f32_e32 v18, v199, v178
	v_exp_f32_e32 v17, v17
	v_min_f32_e32 v18, 0, v18
	v_mul_f32_e32 v18, 0x3fb8aa3b, v18
	v_exp_f32_e32 v18, v18
	v_mul_f32_e32 v17, v29, v17
	v_cndmask_b32_e64 v17, 0, v17, s[36:37]
	v_add_f32_e32 v16, v17, v16
	v_mul_f32_e32 v18, v31, v18
	v_add_f32_e32 v16, v20, v16
	v_cndmask_b32_e64 v19, 0, v18, s[40:41]
	v_add_f32_e32 v16, v19, v16
	v_cvt_pk_bf16_f32 v18, v21, v17
	ds_bpermute_b32 v17, v117, v16
	v_cvt_pk_bf16_f32 v19, v20, v19
	ds_write_b64 v132, v[18:19] offset:36864
	s_and_saveexec_b64 s[76:77], s[6:7]
	s_cbranch_execz .LBB0_466
	s_waitcnt lgkmcnt(1)
	v_add_f32_e32 v16, v16, v17
	ds_write_b32 v133, v16 offset:64512
